# s7: fast softmax path made straight-line (own exp/cvt/row-sum copy, alpha-free), slow max/rescale path moved out of line, guard flag removed from common path
# speedup vs baseline: 1.0333x; 1.0083x over previous
; __device__ __forceinline__ void softmax_rel(f32x16& p0, f32x16& p1, float& m_reg, float& l_reg, f32x16& negm, float& alpha, bool first, bf16x8& pa0, bf16x8& pa1, bf16x8& pa2, bf16x8& pa3) {
;     ...
; #pragma unroll
;     for (int r = 0; r < 16; ++r) { p0[r] = __builtin_amdgcn_exp2f(p0[r]); p1[r] = __builtin_amdgcn_exp2f(p1[r]); }
;     float ps0 = p0[0], ps1 = p1[0], ps2 = p0[8], ps3 = p1[8];
; #pragma unroll
;     for (int r = 1; r < 8; ++r) { ps0 += p0[r]; ps1 += p1[r]; ps2 += p0[8 + r]; ps3 += p1[8 + r]; }
;     l_reg = l_reg * alpha + ((ps0 + ps1) + (ps2 + ps3));
; __device__ __forceinline__ void diff_unit(const bf16_t* __restrict__ proj, bf16_t* __restrict__ mix, float* __restrict__ o1s, const float* __restrict__ g_sub, float lam,
;                                           int rowbase, int T, int h, int qb, char* lds, int widk) {
;     ...
;             { const int kb = bsl * DF_KSZ; bf16x8 k0, k1, k2, k3, k4, k5, k6, k7; const int a0 = ka[0] + kb, a1 = ka[1] + kb, a2 = ka[2] + kb, a3 = ka[3] + kb;
;               KRD(k0, a0, 0); KRD(k1, a0, 4096); KRD(k2, a1, 0); KRD(k3, a1, 4096); KRD(k4, a2, 0); KRD(k5, a2, 4096); KRD(k6, a3, 0); KRD(k7, a3, 4096);
;               asm volatile("s_waitcnt lgkmcnt(6)" ::: "memory"); SBAR();
;               asm volatile("v_mfma_f32_32x32x16_bf16 %0, %1, %2, %3" : "=&v"(p0) : "v"(k0), "v"(qr[0]), "v"(negm));
;               asm volatile("v_mfma_f32_32x32x16_bf16 %0, %1, %2, %3" : "=&v"(p1) : "v"(k1), "v"(qr[0]), "v"(negm)); SBAR();
;               asm volatile("s_waitcnt lgkmcnt(4)" ::: "memory"); SBAR();
;               p0 = __builtin_amdgcn_mfma_f32_32x32x16_bf16(k2, qr[1], p0, 0, 0, 0); p1 = __builtin_amdgcn_mfma_f32_32x32x16_bf16(k3, qr[1], p1, 0, 0, 0); SBAR();
;               asm volatile("s_waitcnt lgkmcnt(2)" ::: "memory"); SBAR();
;               p0 = __builtin_amdgcn_mfma_f32_32x32x16_bf16(k4, qr[2], p0, 0, 0, 0); p1 = __builtin_amdgcn_mfma_f32_32x32x16_bf16(k5, qr[2], p1, 0, 0, 0); SBAR();
;               asm volatile("s_waitcnt lgkmcnt(0)" ::: "memory"); SBAR();
;               p0 = __builtin_amdgcn_mfma_f32_32x32x16_bf16(k6, qr[3], p0, 0, 0, 0); p1 = __builtin_amdgcn_mfma_f32_32x32x16_bf16(k7, qr[3], p1, 0, 0, 0); SBAR(); }
;             __builtin_amdgcn_s_setprio(0);
;             float alpha; bf16x8 pa0, pa1, pa2, pa3;
;             softmax_rel(p0, p1, m_reg, l_reg, negm, alpha, j == 0, pa0, pa1, pa2, pa3);
.LBB0_375:
	s_barrier
	s_setprio 1
	s_waitcnt lgkmcnt(6)
	v_mfma_f32_32x32x16_bf16 v[112:127], v[236:239], v[128:131], v[80:95]
	v_mfma_f32_32x32x16_bf16 v[96:111], v[240:243], v[128:131], v[80:95]
	s_waitcnt lgkmcnt(4)
	s_nop 0
	v_mfma_f32_32x32x16_bf16 v[112:127], v[244:247], v[132:135], v[112:127]
	v_mfma_f32_32x32x16_bf16 v[96:111], v[248:251], v[132:135], v[96:111]
	s_waitcnt lgkmcnt(2)
	v_mfma_f32_32x32x16_bf16 v[112:127], v[216:219], v[136:139], v[112:127]
	v_mfma_f32_32x32x16_bf16 v[96:111], v[220:223], v[136:139], v[96:111]
	s_waitcnt lgkmcnt(0)
	v_mfma_f32_32x32x16_bf16 v[112:127], v[224:227], v[140:143], v[112:127]
	v_mfma_f32_32x32x16_bf16 v[96:111], v[228:231], v[140:143], v[96:111]
	s_setprio 0
	s_nop 10
	s_cmp_lg_u32 s6, 0
	s_cbranch_scc0 .Ldf_slow
	v_exp_f32_e32 v213, v112
	v_exp_f32_e32 v215, v96
	v_exp_f32_e32 v217, v113
	v_exp_f32_e32 v218, v97
	v_exp_f32_e32 v214, v114
	v_exp_f32_e32 v216, v98
	v_exp_f32_e32 v211, v115
	v_exp_f32_e32 v212, v99
	v_exp_f32_e32 v114, v116
	v_exp_f32_e32 v115, v100
	v_exp_f32_e32 v112, v117
	v_exp_f32_e32 v113, v101
	v_exp_f32_e32 v100, v118
	v_exp_f32_e32 v101, v102
	v_exp_f32_e32 v14, v119
	v_exp_f32_e32 v15, v103
	v_exp_f32_e32 v119, v120
	v_exp_f32_e32 v219, v104
	v_exp_f32_e32 v220, v121
	v_exp_f32_e32 v221, v105
	v_exp_f32_e32 v120, v122
	v_exp_f32_e32 v121, v106
	v_exp_f32_e32 v117, v123
	v_exp_f32_e32 v118, v107
	v_exp_f32_e32 v116, v124
	v_exp_f32_e32 v108, v108
	v_exp_f32_e32 v106, v125
	v_exp_f32_e32 v107, v109
	v_exp_f32_e32 v104, v126
	v_exp_f32_e32 v105, v110
	v_exp_f32_e32 v102, v127
	v_exp_f32_e32 v103, v111
	v_cvt_pk_bf16_f32 v96, v213, v217
	v_cvt_pk_bf16_f32 v97, v214, v211
	v_cvt_pk_bf16_f32 v98, v114, v112
	v_cvt_pk_bf16_f32 v99, v100, v14
	v_cvt_pk_bf16_f32 v10, v119, v220
	v_cvt_pk_bf16_f32 v11, v120, v117
	v_cvt_pk_bf16_f32 v12, v116, v106
	v_cvt_pk_bf16_f32 v13, v104, v102
	v_cvt_pk_bf16_f32 v6, v215, v218
	v_cvt_pk_bf16_f32 v7, v216, v212
	v_cvt_pk_bf16_f32 v8, v115, v113
	v_cvt_pk_bf16_f32 v9, v101, v15
	v_cvt_pk_bf16_f32 v2, v219, v221
	v_cvt_pk_bf16_f32 v3, v121, v118
	v_cvt_pk_bf16_f32 v4, v108, v107
	v_cvt_pk_bf16_f32 v5, v105, v103
	v_add_f32_e32 v109, v217, v213
	v_add_f32_e32 v110, v218, v215
	v_add_f32_e32 v111, v220, v119
	v_add_f32_e32 v119, v221, v219
	v_add_f32_e32 v109, v214, v109
	v_add_f32_e32 v110, v216, v110
	v_add_f32_e32 v111, v120, v111
	v_add_f32_e32 v119, v121, v119
	v_add_f32_e32 v109, v211, v109
	v_add_f32_e32 v110, v212, v110
	v_add_f32_e32 v111, v117, v111
	v_add_f32_e32 v117, v118, v119
	v_add_f32_e32 v109, v114, v109
	v_add_f32_e32 v110, v115, v110
	v_add_f32_e32 v111, v116, v111
	v_add_f32_e32 v108, v108, v117
	v_add_f32_e32 v109, v112, v109
	v_add_f32_e32 v110, v113, v110
	v_add_f32_e32 v106, v106, v111
	v_add_f32_e32 v107, v107, v108
	v_add_f32_e32 v100, v100, v109
	v_add_f32_e32 v101, v101, v110
	v_add_f32_e32 v104, v104, v106
	v_add_f32_e32 v105, v105, v107
	v_add_f32_e32 v14, v14, v100
	v_add_f32_e32 v15, v15, v101
	v_add_f32_e32 v100, v102, v104
	v_add_f32_e32 v101, v103, v105
	v_add_f32_e32 v14, v15, v14
	v_add_f32_e32 v15, v101, v100
	v_add_f32_e32 v14, v15, v14
	v_cmp_gt_f32_e32 vcc, 0x71800000, v14
	s_cmp_lg_u64 vcc, exec
	s_cbranch_scc1 .Ldf_fallback
	v_add_f32_e32 v14, v14, v210

; __device__ __forceinline__ void softmax_rel(f32x16& p0, f32x16& p1, float& m_reg, float& l_reg, f32x16& negm, float& alpha, bool first, bf16x8& pa0, bf16x8& pa1, bf16x8& pa2, bf16x8& pa3) {
;     float ma = __builtin_fmaxf(__builtin_fmaxf(p0[0], p0[1]), p0[2]), mb = __builtin_fmaxf(__builtin_fmaxf(p0[8], p0[9]), p0[10]);
;     float mc = __builtin_fmaxf(__builtin_fmaxf(p1[0], p1[1]), p1[2]), md = __builtin_fmaxf(__builtin_fmaxf(p1[8], p1[9]), p1[10]);
;     ma = __builtin_fmaxf(__builtin_fmaxf(ma, p0[3]), p0[4]); mb = __builtin_fmaxf(__builtin_fmaxf(mb, p0[11]), p0[12]); mc = __builtin_fmaxf(__builtin_fmaxf(mc, p1[3]), p1[4]); md = __builtin_fmaxf(__builtin_fmaxf(md, p1[11]), p1[12]);
;     ma = __builtin_fmaxf(__builtin_fmaxf(ma, p0[5]), p0[6]); mb = __builtin_fmaxf(__builtin_fmaxf(mb, p0[13]), p0[14]); mc = __builtin_fmaxf(__builtin_fmaxf(mc, p1[5]), p1[6]); md = __builtin_fmaxf(__builtin_fmaxf(md, p1[13]), p1[14]);
;     ma = __builtin_fmaxf(__builtin_fmaxf(ma, p0[7]), mb); mc = __builtin_fmaxf(__builtin_fmaxf(mc, p1[7]), md);
;     float pmax = __builtin_fmaxf(__builtin_fmaxf(ma, p0[15]), __builtin_fmaxf(mc, p1[15]));
;     { auto rr = __builtin_amdgcn_permlane32_swap(__float_as_uint(pmax), __float_as_uint(pmax), false, false); pmax = __builtin_fmaxf(__uint_as_float(rr[0]), __uint_as_float(rr[1])); }
;     alpha = 1.f;
;     if (__builtin_expect(first || !__all(pmax <= THR), 0)) {
;         const float dl = first ? pmax : fmaxf(pmax, 0.f);
;         m_reg += dl; alpha = first ? 1.f : __builtin_amdgcn_exp2f(-dl);
.Ldf_slow:
	v_max_f32_e32 v3, v97, v97
	v_max_f32_e32 v4, v96, v96
	v_max3_f32 v1, v112, v113, v114
	v_max3_f32 v2, v120, v121, v122
	v_max_f32_e32 v3, v4, v3
	v_max3_f32 v4, v104, v105, v106
	v_max3_f32 v1, v1, v115, v116
	v_max3_f32 v2, v2, v123, v124
	v_max3_f32 v3, v3, v98, v99
	v_max3_f32 v4, v4, v107, v108
	v_max3_f32 v1, v1, v117, v118
	v_max3_f32 v2, v2, v125, v126
	v_max3_f32 v3, v3, v100, v101
	v_max3_f32 v4, v4, v109, v110
	v_max3_f32 v1, v1, v119, v2
	v_max3_f32 v2, v3, v102, v103
	v_max3_f32 v2, v2, v4, v111
	v_max3_f32 v1, v1, v127, v2
	v_mov_b32_e32 v2, v1
	s_nop 1
	v_permlane32_swap_b32_e32 v1, v2
	s_cmp_eq_u32 s6, 0
	v_max_f32_e32 v2, v2, v2
	v_max_f32_e32 v1, v1, v1
	s_cselect_b64 s[0:1], -1, 0
	s_cmp_lg_u32 s6, 0
	v_max_f32_e32 v1, v1, v2
	s_cbranch_scc0 .LBB0_392
	v_cmp_ge_f32_e32 vcc, s63, v1
	s_cmp_lg_u64 vcc, exec
	s_mov_b64 s[50:51], 0
	s_mov_b64 s[48:49], 0
	s_cbranch_scc1 .LBB0_393
	s_and_b64 vcc, exec, s[50:51]
	s_cbranch_vccnz .LBB0_394

; __device__ __forceinline__ void softmax_rel(f32x16& p0, f32x16& p1, float& m_reg, float& l_reg, f32x16& negm, float& alpha, bool first, bf16x8& pa0, bf16x8& pa1, bf16x8& pa2, bf16x8& pa3) {
;     ...
;     float ps0 = p0[0], ps1 = p1[0], ps2 = p0[8], ps3 = p1[8];
; #pragma unroll
;     for (int r = 1; r < 8; ++r) { ps0 += p0[r]; ps1 += p1[r]; ps2 += p0[8 + r]; ps3 += p1[8 + r]; }
;     l_reg = l_reg * alpha + ((ps0 + ps1) + (ps2 + ps3));
.LBB0_384:
	v_add_f32_e32 v109, v217, v213
	v_add_f32_e32 v110, v218, v215
	v_add_f32_e32 v111, v220, v119
	v_add_f32_e32 v119, v221, v219
	v_add_f32_e32 v109, v214, v109
	v_add_f32_e32 v110, v216, v110
	v_add_f32_e32 v111, v120, v111
	v_add_f32_e32 v119, v121, v119
	v_add_f32_e32 v109, v211, v109
	v_add_f32_e32 v110, v212, v110
	v_add_f32_e32 v111, v117, v111
	v_add_f32_e32 v117, v118, v119
	v_add_f32_e32 v109, v114, v109
	v_add_f32_e32 v110, v115, v110
	v_add_f32_e32 v111, v116, v111
	v_add_f32_e32 v108, v108, v117
	v_add_f32_e32 v109, v112, v109
	v_add_f32_e32 v110, v113, v110
	v_add_f32_e32 v106, v106, v111
	v_add_f32_e32 v107, v107, v108
	v_add_f32_e32 v100, v100, v109
	v_add_f32_e32 v101, v101, v110
	v_add_f32_e32 v104, v104, v106
	v_add_f32_e32 v105, v105, v107
	v_add_f32_e32 v14, v14, v100
	v_add_f32_e32 v15, v15, v101
	v_add_f32_e32 v100, v102, v104
	v_add_f32_e32 v101, v103, v105
	v_add_f32_e32 v14, v15, v14
	v_add_f32_e32 v15, v101, v100
	v_add_f32_e32 v14, v15, v14
	v_fmac_f32_e32 v14, v210, v1
	s_branch .Ldf_tail
